# attention: waves 0-3 at priority 2, waves 4-7 at priority 1 in the step loop (reverse split)
# speedup vs baseline: 1.0036x; 1.0036x over previous
; #define GAS __attribute__((address_space(1)))
; #define AT_KRD(dst, koff, ks0) do { const LAS unsigned char* Kl = Kr + (koff); \
;             _Pragma("unroll") for (int ks = 0; ks < 3; ++ks) { dst[2 * ks] = *(const LAS bf16x8_t*)(Kl + ((ks0) + ks) * 32); dst[2 * ks + 1] = *(const LAS bf16x8_t*)(Kl + 32 * AT_KP + ((ks0) + ks) * 32); } } while (0)
; #define AT_KMM(P0, P1, src, ks0) do { _Pragma("unroll") for (int ks = 0; ks < 3; ++ks) { \
;             P0 = __builtin_amdgcn_mfma_f32_32x32x16_bf16(src[2 * ks], qf[(ks0) + ks], P0, 0, 0, 0); P1 = __builtin_amdgcn_mfma_f32_32x32x16_bf16(src[2 * ks + 1], qf[(ks0) + ks], P1, 0, 0, 0); } } while (0)
; #define AT_ZERO(P0, P1) do { _Pragma("unroll") for (int r = 0; r < 16; ++r) { P0[r] = 0.f; P1[r] = 0.f; } } while (0)
; __device__ __forceinline__ void ph_attn(Frame& F) {
;     ...
;         { const bf16* qp = Qb + (bh * TQK + tq0 + wave * 32 + r32) * 96 + hi * 8;
; #pragma unroll
;           for (int ks = 0; ks < 6; ++ks) qf[ks] = *(const GAS bf16x8_t*)(qp + ks * 16); }
;         f32x16 o0, o1, pA0, pA1, pB0, pB1;
;         bf16x8_t pk0, pk1, pk2_, pk3;
;         bf16x8_t vf[8], kf[6];
;         { const v4u z = (v4u){0u, 0u, 0u, 0u}; pk0 = __builtin_bit_cast(bf16x8_t, z); pk1 = pk0; pk2_ = pk0; pk3 = pk0;
; #pragma unroll
;           for (int j = 0; j < 8; ++j) vf[j] = pk0; }
; #pragma unroll
;         for (int r = 0; r < 16; ++r) { o0[r] = 0.f; o1[r] = 0.f; pB0[r] = 0.f; pB1[r] = 0.f; }
;         float m_run = -1e30f, l_run = 0.f;
;     ...
;         asm volatile("s_waitcnt vmcnt(0)" ::: "memory");
;         __syncthreads();
;         AT_DMA(0, 0, 0, 0); AT_DMA(1, AT_KB, 1, AT_VB); AT_DMA(2, 2 * AT_KB, 0, 0); AT_DMA(3, 3 * AT_KB, 1, AT_VB);
;         asm volatile("s_waitcnt vmcnt(0)" ::: "memory");
;         __syncthreads();
;     ...
;         { bf16x8_t kg[6]; AT_KRD(kf, 0, 0); AT_KRD(kg, 0, 3); AT_ZERO(pA0, pA1); AT_KMM(pA0, pA1, kf, 0); AT_KMM(pA0, pA1, kg, 3); AT_KRD(kf, AT_KB, 0); }
;         __syncthreads();
;         if (AT_PRIO && __builtin_amdgcn_readfirstlane(wave) >= 4) __builtin_amdgcn_s_setprio(1);
.LBB0_996:
	s_and_b32 s35, s13, 7
	s_lshl_b32 s11, s12, 3
	s_or_b32 s11, s11, s35
	v_add_u32_e32 v2, s10, v201
	s_mul_hi_i32 s12, s11, 0x18c000
	s_mul_i32 s13, s11, 0x18c000
	s_mul_hi_i32 s14, s11, 0x108000
	s_mul_i32 s15, s11, 0x108000
	v_mad_i64_i32 v[4:5], s[10:11], s11, v207, v[2:3]
	v_mad_u64_u32 v[6:7], s[10:11], v4, s20, v[196:197]
	v_mad_i32_i24 v7, v5, s20, v7
	global_load_dwordx4 v[100:103], v[6:7], off
	global_load_dwordx4 v[104:107], v[6:7], off offset:32
	global_load_dwordx4 v[108:111], v[6:7], off offset:64
	global_load_dwordx4 v[112:115], v[6:7], off offset:96
	global_load_dwordx4 v[116:119], v[6:7], off offset:128
	global_load_dwordx4 v[120:123], v[6:7], off offset:160
	s_add_u32 s10, s16, s13
	s_addc_u32 s11, s17, s12
	s_add_u32 s12, s18, s15
	s_addc_u32 s13, s19, s14
	s_and_b64 s[14:15], s[4:5], exec
	s_mov_b32 m0, s22
	v_lshl_add_u64 v[4:5], s[10:11], 0, v[190:191]
	s_cselect_b32 s15, s11, s13
	s_cselect_b32 s14, s10, s12
	s_waitcnt vmcnt(6)
	s_barrier
	global_load_lds_dwordx4 v[4:5], off
	v_lshl_add_u64 v[4:5], s[14:15], 0, v[192:193]
	s_add_u32 s14, s10, 0x3000
	s_addc_u32 s15, s11, 0
	s_add_u32 s38, s12, 0x2000
	s_mov_b32 m0, s21
	s_addc_u32 s39, s13, 0
	global_load_lds_dwordx4 v[4:5], off
	v_lshl_add_u64 v[4:5], s[12:13], 0, v[194:195]
	s_mov_b32 m0, s31
	s_and_b64 s[40:41], s[4:5], exec
	global_load_lds_dwordx4 v[4:5], off
	v_lshl_add_u64 v[6:7], s[14:15], 0, v[190:191]
	s_mov_b32 m0, s24
	s_cselect_b32 s15, s15, s39
	s_cselect_b32 s14, s14, s38
	global_load_lds_dwordx4 v[6:7], off
	v_lshl_add_u64 v[6:7], s[14:15], 0, v[192:193]
	s_add_u32 s14, s10, 0x6000
	s_mov_b32 m0, s25
	s_addc_u32 s15, s11, 0
	global_load_lds_dwordx4 v[6:7], off
	v_lshl_add_u64 v[6:7], s[38:39], 0, v[194:195]
	s_mov_b32 m0, s26
	s_and_b64 s[40:41], s[4:5], exec
	global_load_lds_dwordx4 v[6:7], off
	v_lshl_add_u64 v[8:9], s[14:15], 0, v[190:191]
	s_mov_b32 m0, s27
	s_cselect_b32 s15, s15, s13
	s_cselect_b32 s14, s14, s12
	global_load_lds_dwordx4 v[8:9], off
	v_lshl_add_u64 v[8:9], s[14:15], 0, v[192:193]
	s_add_u32 s14, s10, 0x9000
	s_mov_b32 m0, s28
	s_addc_u32 s15, s11, 0
	global_load_lds_dwordx4 v[8:9], off
	s_mov_b32 m0, s31
	s_and_b64 s[40:41], s[4:5], exec
	global_load_lds_dwordx4 v[4:5], off
	v_lshl_add_u64 v[4:5], s[14:15], 0, v[190:191]
	s_mov_b32 m0, s29
	s_cselect_b32 s15, s15, s39
	s_cselect_b32 s14, s14, s38
	global_load_lds_dwordx4 v[4:5], off
	v_lshl_add_u64 v[4:5], s[14:15], 0, v[192:193]
	s_mov_b32 m0, s30
	v_readfirstlane_b32 s14, v206
	global_load_lds_dwordx4 v[4:5], off
	s_mov_b32 m0, s26
	s_cmp_lt_i32 s14, 4
	global_load_lds_dwordx4 v[6:7], off
	s_waitcnt vmcnt(0)
	s_waitcnt vmcnt(0) lgkmcnt(0)
	s_barrier
	ds_read_b128 v[4:7], v189
	ds_read_b128 v[8:11], v189 offset:32
	s_waitcnt lgkmcnt(1)
	v_mfma_f32_32x32x16_bf16 v[52:67], v[4:7], v[100:103], 0
	ds_read_b128 v[4:7], v189 offset:6656
	ds_read_b128 v[12:15], v189 offset:6688
	s_waitcnt lgkmcnt(1)
	v_mfma_f32_32x32x16_bf16 v[36:51], v[4:7], v[100:103], 0
	v_mfma_f32_32x32x16_bf16 v[52:67], v[8:11], v[104:107], v[52:67]
	ds_read_b128 v[4:7], v189 offset:64
	ds_read_b128 v[8:11], v189 offset:96
	s_waitcnt lgkmcnt(2)
	v_mfma_f32_32x32x16_bf16 v[36:51], v[12:15], v[104:107], v[36:51]
	s_waitcnt lgkmcnt(1)
	v_mfma_f32_32x32x16_bf16 v[52:67], v[4:7], v[108:111], v[52:67]
	ds_read_b128 v[4:7], v189 offset:6720
	ds_read_b128 v[12:15], v189 offset:6752
	s_waitcnt lgkmcnt(1)
	v_mfma_f32_32x32x16_bf16 v[36:51], v[4:7], v[108:111], v[36:51]
	s_waitcnt lgkmcnt(0)
	v_mfma_f32_32x32x16_bf16 v[36:51], v[12:15], v[112:115], v[36:51]
	v_mfma_f32_32x32x16_bf16 v[52:67], v[8:11], v[112:115], v[52:67]
	ds_read_b128 v[4:7], v189 offset:6784
	ds_read_b128 v[8:11], v189 offset:6816
	s_waitcnt lgkmcnt(1)
	v_mfma_f32_32x32x16_bf16 v[36:51], v[4:7], v[116:119], v[36:51]
	ds_read_b128 v[4:7], v189 offset:128
	ds_read_b128 v[12:15], v189 offset:160
	ds_read_b128 v[132:135], v189 offset:13312
	ds_read_b128 v[128:131], v189 offset:13344
	ds_read_b128 v[136:139], v189 offset:19968
	ds_read_b128 v[124:127], v189 offset:13376
	ds_read_b128 v[144:147], v189 offset:20000
	ds_read_b128 v[140:143], v189 offset:20032
	s_waitcnt lgkmcnt(0)
	s_barrier
	v_mfma_f32_32x32x16_bf16 v[52:67], v[4:7], v[116:119], v[52:67]
	v_mfma_f32_32x32x16_bf16 v[36:51], v[8:11], v[120:123], v[36:51]
	v_mfma_f32_32x32x16_bf16 v[52:67], v[12:15], v[120:123], v[52:67]
	s_cbranch_scc1 .LBB0_998
	v_readfirstlane_b32 s99, v236
	s_lshr_b32 s99, s99, 8
	s_cmp_lg_u32 s99, 0
	s_cbranch_scc1 .Lprio_young
	s_setprio 2
	s_branch .LBB0_998
.Lprio_young:
	s_setprio 1
